# prenorm copy1 software pipelining: next iteration x-row loads issued before reduction tail
# speedup vs baseline: 1.0525x; 1.0002x over previous
.LBB0_199:
	s_ashr_i32 s5, s3, 6
	s_add_i32 s10, s5, s40
	s_cmp_ge_i32 s10, s28
	s_cbranch_scc1 .LBB0_218
	v_readlane_b32 s6, v255, 14
	v_readlane_b32 s7, v255, 15
	s_load_dwordx2 s[12:13], s[6:7], 0x0
	s_nop 0
	s_load_dwordx2 s[6:7], s[0:1], 0xc8
	v_lshlrev_b32_e32 v0, 2, v2
	v_and_b32_e32 v66, 0xfc, v0
	v_lshlrev_b32_e32 v0, 2, v66
	v_and_b32_e32 v3, 64, v228
	s_waitcnt lgkmcnt(0)
	s_add_u32 s3, s6, 0x103000
	s_addc_u32 s4, s7, 0
	v_lshl_add_u64 v[4:5], s[6:7], 0, v[0:1]
	s_mov_b64 s[6:7], 0xbb00000
	v_lshl_add_u64 v[68:69], v[4:5], 0, s[6:7]
	v_add_u32_e32 v3, 64, v3
	v_xor_b32_e32 v4, 1, v228
	v_cmp_lt_i32_e32 vcc, v4, v3
	v_readlane_b32 s6, v255, 52
	v_readlane_b32 s7, v255, 53
	v_cndmask_b32_e32 v4, v228, v4, vcc
	v_lshlrev_b32_e32 v67, 2, v4
	v_xor_b32_e32 v4, 2, v228
	v_cmp_lt_i32_e32 vcc, v4, v3
	v_lshl_add_u64 v[76:77], s[6:7], 0, v[0:1]
	v_readlane_b32 s6, v254, 46
	v_cndmask_b32_e32 v4, v228, v4, vcc
	v_lshlrev_b32_e32 v71, 2, v4
	v_xor_b32_e32 v4, 4, v228
	v_cmp_lt_i32_e32 vcc, v4, v3
	s_ashr_i32 s11, s10, 31
	s_add_i32 s74, s6, s5
	v_cndmask_b32_e32 v4, v228, v4, vcc
	v_lshlrev_b32_e32 v73, 2, v4
	v_xor_b32_e32 v4, 8, v228
	v_cmp_lt_i32_e32 vcc, v4, v3
	s_lshl_b64 s[6:7], s[10:11], 11
	v_readlane_b32 s5, v255, 54
	v_cndmask_b32_e32 v4, v228, v4, vcc
	v_lshlrev_b32_e32 v75, 2, v4
	v_xor_b32_e32 v4, 16, v228
	v_cmp_lt_i32_e32 vcc, v4, v3
	v_and_b32_e32 v0, 63, v2
	s_add_u32 s6, s5, s6
	v_cndmask_b32_e32 v4, v228, v4, vcc
	v_lshlrev_b32_e32 v80, 2, v4
	v_xor_b32_e32 v4, 32, v228
	v_cmp_lt_i32_e32 vcc, v4, v3
	v_readlane_b32 s5, v255, 55
	v_lshlrev_b32_e32 v0, 3, v0
	v_cndmask_b32_e32 v3, v228, v4, vcc
	s_addc_u32 s7, s5, s7
	v_or_b32_e32 v70, 0x100, v66
	v_or_b32_e32 v72, 0x200, v66
	v_or_b32_e32 v74, 0x300, v66
	v_lshlrev_b32_e32 v81, 2, v3
	v_lshl_add_u64 v[78:79], s[6:7], 0, v[0:1]
	v_lshlrev_b32_e32 v0, 2, v66
	s_mov_b32 s100, 0
	s_branch .LBB0_202

.LBB0_202:
	s_add_i32 s6, s42, s74
	s_add_i32 s17, s74, 0x4000
	s_add_i32 s16, s6, 0x4000
	s_cmp_lt_i32 s16, s28
	s_cselect_b64 s[14:15], -1, 0
	s_and_b64 s[18:19], s[14:15], exec
	s_cselect_b32 s5, s16, s17
	s_cmpk_lt_i32 s17, 0x4000
	s_cselect_b32 s19, s11, 0
	s_cselect_b32 s18, s10, s74
	s_cselect_b32 s7, s13, s9
	s_cselect_b32 s20, s12, s8
	s_lshl_b64 s[18:19], s[18:19], 12
	s_add_u32 s18, s20, s18
	s_addc_u32 s19, s7, s19
	s_add_i32 s7, s5, 0xffffc000
	s_ashr_i32 s20, s5, 31
	s_cmpk_lt_i32 s5, 0x4000
	s_cselect_b32 s21, s20, 0
	s_cselect_b32 s20, s5, s7
	s_cselect_b32 s7, s13, s9
	s_cselect_b32 s22, s12, s8
	s_lshl_b64 s[20:21], s[20:21], 12
	s_add_u32 s20, s22, s20
	s_addc_u32 s21, s7, s21
	s_cmp_eq_u32 s100, 1
	s_mov_b64 s[100:101], s[18:19]
	s_cbranch_scc1 .Lpn1_pf_top
	global_load_dwordx4 v[18:21], v0, s[18:19] nt
	global_load_dwordx4 v[22:25], v0, s[18:19] offset:1024 nt
	global_load_dwordx4 v[62:65], v0, s[20:21] nt
	global_load_dwordx4 v[54:57], v0, s[20:21] offset:1024 nt
	global_load_dwordx4 v[26:29], v0, s[18:19] offset:2048 nt
	global_load_dwordx4 v[30:33], v0, s[18:19] offset:3072 nt
	global_load_dwordx4 v[58:61], v0, s[20:21] offset:2048 nt
	global_load_dwordx4 v[50:53], v0, s[20:21] offset:3072 nt
	v_readlane_b32 s20, v255, 10
	v_readlane_b32 s21, v255, 11
	s_mov_b64 s[18:19], -1
	s_and_b64 vcc, exec, s[20:21]
	s_cbranch_vccz .LBB0_208
	s_cmpk_lt_i32 s17, 0x4000
	s_waitcnt vmcnt(7)
	v_mov_b32_e32 v2, v18
	v_mov_b32_e32 v3, v19
	v_mov_b32_e32 v4, v20
	v_mov_b32_e32 v5, v21
	s_waitcnt vmcnt(6)
	v_mov_b32_e32 v6, v22
	v_mov_b32_e32 v7, v23
	v_mov_b32_e32 v8, v24
	v_mov_b32_e32 v9, v25
	s_waitcnt vmcnt(3)
	v_mov_b32_e32 v10, v26
	v_mov_b32_e32 v11, v27
	v_mov_b32_e32 v12, v28
	v_mov_b32_e32 v13, v29
	s_waitcnt vmcnt(2)
	v_mov_b32_e32 v14, v30
	v_mov_b32_e32 v15, v31
	v_mov_b32_e32 v16, v32
	v_mov_b32_e32 v17, v33
	s_cbranch_scc1 .LBB0_205
	s_lshl_b64 s[18:19], s[74:75], 12
	v_lshl_add_u64 v[98:99], v[68:69], 0, s[18:19]
	v_add_co_u32_e32 v46, vcc, 0x400000, v98
	global_load_dwordx4 v[2:5], v[98:99], off
	global_load_dwordx4 v[6:9], v[98:99], off offset:1024
	global_load_dwordx4 v[10:13], v[98:99], off offset:2048
	global_load_dwordx4 v[14:17], v[98:99], off offset:3072
	v_addc_co_u32_e32 v47, vcc, 0, v99, vcc
	v_add_co_u32_e32 v94, vcc, 0x800000, v98
	global_load_dwordx4 v[34:37], v[46:47], off
	global_load_dwordx4 v[38:41], v[46:47], off offset:1024
	global_load_dwordx4 v[42:45], v[46:47], off offset:2048
	s_nop 0
	global_load_dwordx4 v[46:49], v[46:47], off offset:3072
	v_addc_co_u32_e32 v95, vcc, 0, v99, vcc
	v_add_co_u32_e32 v110, vcc, 0xc00000, v98
	global_load_dwordx4 v[82:85], v[94:95], off
	global_load_dwordx4 v[86:89], v[94:95], off offset:1024
	global_load_dwordx4 v[90:93], v[94:95], off offset:2048
	s_nop 0
	global_load_dwordx4 v[94:97], v[94:95], off offset:3072
	v_addc_co_u32_e32 v111, vcc, 0, v99, vcc
	global_load_dwordx4 v[98:101], v[110:111], off
	global_load_dwordx4 v[102:105], v[110:111], off offset:1024
	global_load_dwordx4 v[106:109], v[110:111], off offset:2048
	s_nop 0
	global_load_dwordx4 v[110:113], v[110:111], off offset:3072
	s_waitcnt vmcnt(15)
	v_pk_add_f32 v[4:5], v[20:21], v[4:5]
	v_pk_add_f32 v[2:3], v[18:19], v[2:3]
	s_waitcnt vmcnt(14)
	v_pk_add_f32 v[8:9], v[24:25], v[8:9]
	v_pk_add_f32 v[6:7], v[22:23], v[6:7]
	s_waitcnt vmcnt(13)
	v_pk_add_f32 v[12:13], v[28:29], v[12:13]
	v_pk_add_f32 v[10:11], v[26:27], v[10:11]
	s_waitcnt vmcnt(12)
	v_pk_add_f32 v[16:17], v[32:33], v[16:17]
	v_pk_add_f32 v[14:15], v[30:31], v[14:15]
	s_waitcnt vmcnt(11)
	v_pk_add_f32 v[4:5], v[4:5], v[36:37]
	v_pk_add_f32 v[2:3], v[2:3], v[34:35]
	s_waitcnt vmcnt(10)
	v_pk_add_f32 v[8:9], v[8:9], v[40:41]
	v_pk_add_f32 v[6:7], v[6:7], v[38:39]
	s_waitcnt vmcnt(9)
	v_pk_add_f32 v[12:13], v[12:13], v[44:45]
	v_pk_add_f32 v[10:11], v[10:11], v[42:43]
	s_waitcnt vmcnt(8)
	v_pk_add_f32 v[16:17], v[16:17], v[48:49]
	v_pk_add_f32 v[14:15], v[14:15], v[46:47]
	s_waitcnt vmcnt(7)
	v_pk_add_f32 v[4:5], v[4:5], v[84:85]
	v_pk_add_f32 v[2:3], v[2:3], v[82:83]
	s_waitcnt vmcnt(6)
	v_pk_add_f32 v[8:9], v[8:9], v[88:89]
	v_pk_add_f32 v[6:7], v[6:7], v[86:87]
	s_waitcnt vmcnt(5)
	v_pk_add_f32 v[12:13], v[12:13], v[92:93]
	v_pk_add_f32 v[10:11], v[10:11], v[90:91]
	s_waitcnt vmcnt(4)
	v_pk_add_f32 v[16:17], v[16:17], v[96:97]
	v_pk_add_f32 v[14:15], v[14:15], v[94:95]
	s_waitcnt vmcnt(3)
	v_pk_add_f32 v[4:5], v[4:5], v[100:101]
	v_pk_add_f32 v[2:3], v[2:3], v[98:99]
	s_waitcnt vmcnt(2)
	v_pk_add_f32 v[8:9], v[8:9], v[104:105]
	v_pk_add_f32 v[6:7], v[6:7], v[102:103]
	s_waitcnt vmcnt(1)
	v_pk_add_f32 v[12:13], v[12:13], v[108:109]
	v_pk_add_f32 v[10:11], v[10:11], v[106:107]
	s_waitcnt vmcnt(0)
	v_pk_add_f32 v[16:17], v[16:17], v[112:113]
	v_pk_add_f32 v[14:15], v[14:15], v[110:111]
	v_lshl_add_u64 v[34:35], v[76:77], 0, s[18:19]
	global_store_dwordx4 v[34:35], v[2:5], off
	global_store_dwordx4 v[34:35], v[6:9], off offset:1024
	global_store_dwordx4 v[34:35], v[10:13], off offset:2048
	global_store_dwordx4 v[34:35], v[14:17], off offset:3072

.LBB0_210:
	s_nop 0
	v_pk_mul_f32 v[140:141], v[48:49], v[48:49]
	s_nop 0
	v_pk_mul_f32 v[142:143], v[46:47], v[46:47]
	v_pk_mul_f32 v[130:131], v[8:9], v[8:9]
	v_pk_mul_f32 v[132:133], v[6:7], v[6:7]
	v_pk_mov_b32 v[144:145], v[142:143], v[140:141] op_sel:[1,0]
	v_mov_b32_e32 v143, v141
	v_pk_add_f32 v[140:141], v[144:145], v[142:143]
	v_pk_mov_b32 v[142:143], v[132:133], v[130:131] op_sel:[1,0]
	v_mov_b32_e32 v133, v131
	s_min_i32 s6, s17, 0x4000
	v_pk_mul_f32 v[134:135], v[4:5], v[4:5]
	v_pk_mul_f32 v[136:137], v[2:3], v[2:3]
	v_pk_add_f32 v[130:131], v[142:143], v[132:133]
	s_ashr_i32 s6, s6, 12
	v_readlane_b32 s17, v255, 30
	s_min_i32 s5, s5, 0x4000
	v_pk_mov_b32 v[138:139], v[136:137], v[134:135] op_sel:[1,0]
	v_mov_b32_e32 v137, v135
	v_pk_add_f32 v[130:131], v[130:131], v[130:131] op_sel_hi:[0,1]
	s_add_i32 s6, s6, s17
	s_ashr_i32 s5, s5, 12
	v_pk_add_f32 v[134:135], v[138:139], v[136:137]
	v_pk_mul_f32 v[136:137], v[44:45], v[44:45]
	v_pk_mul_f32 v[138:139], v[42:43], v[42:43]
	v_mul_f32_e32 v130, v10, v10
	s_mulk_i32 s6, 0x1800
	s_add_i32 s5, s5, s17
	v_pk_mov_b32 v[132:133], v[138:139], v[136:137] op_sel:[1,0]
	v_mov_b32_e32 v139, v137
	v_pk_fma_f32 v[136:137], v[10:11], v[10:11], v[130:131] op_sel_hi:[1,1,0]
	v_mul_f32_e32 v130, v12, v12
	s_ashr_i32 s7, s6, 31
	s_mul_i32 s18, s5, 0x1800
	v_pk_add_f32 v[132:133], v[132:133], v[138:139]
	v_pk_fma_f32 v[138:139], v[12:13], v[12:13], v[130:131] op_sel_hi:[1,1,0]
	v_mul_f32_e32 v130, v38, v38
	s_ashr_i32 s19, s18, 31
	s_lshl_b64 s[6:7], s[6:7], 2
	v_pk_fma_f32 v[142:143], v[38:39], v[38:39], v[130:131] op_sel_hi:[1,1,0]
	v_mul_f32_e32 v130, v40, v40
	s_add_u32 s20, s3, s6
	v_pk_add_f32 v[134:135], v[134:135], v[134:135] op_sel_hi:[0,1]
	v_pk_add_f32 v[140:141], v[140:141], v[140:141] op_sel_hi:[0,1]
	v_pk_add_f32 v[132:133], v[132:133], v[132:133] op_sel_hi:[0,1]
	v_pk_fma_f32 v[144:145], v[40:41], v[40:41], v[130:131] op_sel_hi:[1,1,0]
	s_addc_u32 s21, s4, s7
	s_lshl_b64 s[6:7], s[18:19], 2
	v_mul_f32_e32 v136, v14, v14
	v_mul_f32_e32 v138, v15, v15
	v_mul_f32_e32 v134, v16, v16
	v_mul_f32_e32 v130, v17, v17
	v_mul_f32_e32 v142, v34, v34
	v_mul_f32_e32 v144, v35, v35
	v_mul_f32_e32 v140, v36, v36
	v_mul_f32_e32 v132, v37, v37
	s_add_u32 s18, s3, s6
	v_pk_add_f32 v[136:137], v[136:137], v[138:139]
	v_pk_add_f32 v[130:131], v[134:135], v[130:131]
	v_pk_add_f32 v[134:135], v[142:143], v[144:145]
	v_pk_add_f32 v[132:133], v[140:141], v[132:133]
	s_addc_u32 s19, s4, s7
	v_pk_add_f32 v[130:131], v[136:137], v[130:131]
	v_pk_add_f32 v[132:133], v[134:135], v[132:133]
	v_mov_b32_e32 v135, v130
	v_mov_b32_e32 v134, v132
	v_mov_b32_e32 v130, v133
	s_add_u32 s24, s20, 0x1000
	v_pk_add_f32 v[130:131], v[134:135], v[130:131]
	s_addc_u32 s25, s21, 0
	global_load_dwordx4 v[134:137], v0, s[20:21]
	global_load_dwordx4 v[138:141], v0, s[24:25]
	s_add_u32 s22, s18, 0x1000
	s_addc_u32 s23, s19, 0
	global_load_dwordx4 v[82:85], v0, s[20:21] offset:1024
	global_load_dwordx4 v[86:89], v0, s[24:25] offset:1024
	global_load_dwordx4 v[90:93], v0, s[20:21] offset:2048
	global_load_dwordx4 v[94:97], v0, s[24:25] offset:2048
	global_load_dwordx4 v[98:101], v0, s[20:21] offset:3072
	global_load_dwordx4 v[102:105], v0, s[24:25] offset:3072
	global_load_dwordx4 v[106:109], v0, s[18:19]
	global_load_dwordx4 v[110:113], v0, s[22:23]
	global_load_dwordx4 v[114:117], v0, s[18:19] offset:1024
	global_load_dwordx4 v[118:121], v0, s[22:23] offset:1024
	global_load_dwordx4 v[122:125], v0, s[18:19] offset:2048
	global_load_dwordx4 v[126:129], v0, s[22:23] offset:2048
	global_load_dwordx4 v[146:149], v0, s[18:19] offset:3072
	global_load_dwordx4 v[150:153], v0, s[22:23] offset:3072
	s_add_i32 s6, s16, s26
	s_cmpk_lt_i32 s6, 0x4000
	s_cbranch_scc0 .Lpn1_nopf
	s_lshl_b32 s6, s26, 12
	s_add_u32 s18, s100, s6
	s_addc_u32 s19, s101, 0
	s_lshl_b32 s6, s42, 12
	s_add_u32 s20, s18, s6
	s_addc_u32 s21, s19, 0
	global_load_dwordx4 v[18:21], v0, s[18:19] nt
	global_load_dwordx4 v[22:25], v0, s[18:19] offset:1024 nt
	global_load_dwordx4 v[62:65], v0, s[20:21] nt
	global_load_dwordx4 v[54:57], v0, s[20:21] offset:1024 nt
	global_load_dwordx4 v[26:29], v0, s[18:19] offset:2048 nt
	global_load_dwordx4 v[30:33], v0, s[18:19] offset:3072 nt
	global_load_dwordx4 v[58:61], v0, s[20:21] offset:2048 nt
	global_load_dwordx4 v[50:53], v0, s[20:21] offset:3072 nt
	s_mov_b32 s100, 1
.Lpn1_nopf:
	s_ashr_i32 s17, s16, 31
	v_readlane_b32 s5, v255, 54
	s_lshl_b64 s[6:7], s[16:17], 11
	v_lshlrev_b32_e32 v142, 1, v66
	s_add_u32 s16, s5, s6
	v_readlane_b32 s5, v255, 55
	ds_bpermute_b32 v133, v67, v131
	ds_bpermute_b32 v132, v67, v130
	s_addc_u32 s17, s5, s7
	s_waitcnt lgkmcnt(0)
	v_pk_add_f32 v[130:131], v[130:131], v[132:133]
	ds_bpermute_b32 v133, v71, v131
	ds_bpermute_b32 v132, v71, v130
	s_mov_b32 s6, 0x3a800000
	s_waitcnt lgkmcnt(0)
	v_pk_add_f32 v[130:131], v[130:131], v[132:133]
	ds_bpermute_b32 v133, v73, v131
	ds_bpermute_b32 v132, v73, v130
	s_waitcnt lgkmcnt(0)
	v_pk_add_f32 v[130:131], v[130:131], v[132:133]
	ds_bpermute_b32 v133, v75, v131
	ds_bpermute_b32 v132, v75, v130
	s_waitcnt lgkmcnt(0)
	v_pk_add_f32 v[130:131], v[130:131], v[132:133]
	ds_bpermute_b32 v133, v80, v131
	ds_bpermute_b32 v132, v80, v130
	s_waitcnt lgkmcnt(0)
	v_pk_add_f32 v[130:131], v[130:131], v[132:133]
	ds_bpermute_b32 v133, v81, v131
	ds_bpermute_b32 v132, v81, v130
	s_waitcnt lgkmcnt(0)
	v_pk_add_f32 v[130:131], v[130:131], v[132:133]
	s_nop 0
	v_pk_fma_f32 v[130:131], v[130:131], s[6:7], v[190:191] op_sel_hi:[1,0,0]
	s_cmp_eq_u32 s100, 1
	s_cbranch_scc1 .Lpn1_w8
	s_waitcnt vmcnt(0)
	s_branch .Lpn1_wj
.Lpn1_w8:
	s_waitcnt vmcnt(8)
.Lpn1_wj:
	v_mul_f32_e32 v132, 0x4b800000, v131
	v_cmp_gt_f32_e32 vcc, s96, v131
	v_cmp_gt_f32_e64 s[6:7], s96, v130
	v_pk_add_f32 v[140:141], v[140:141], 1.0 op_sel_hi:[1,0]
	v_pk_add_f32 v[138:139], v[138:139], 1.0 op_sel_hi:[1,0]
	v_cndmask_b32_e32 v131, v131, v132, vcc
	v_rsq_f32_e32 v131, v131
	v_mul_f32_e32 v132, 0x4b800000, v130
	v_cndmask_b32_e64 v130, v130, v132, s[6:7]
	v_rsq_f32_e32 v130, v130
	v_mul_f32_e32 v132, 0x45800000, v131
	v_cndmask_b32_e32 v132, v131, v132, vcc
	v_mul_f32_e32 v131, 0x45800000, v130
	v_cndmask_b32_e64 v130, v130, v131, s[6:7]
	v_pk_add_f32 v[88:89], v[88:89], 1.0 op_sel_hi:[1,0]
	v_pk_add_f32 v[86:87], v[86:87], 1.0 op_sel_hi:[1,0]
	v_pk_add_f32 v[96:97], v[96:97], 1.0 op_sel_hi:[1,0]
	v_pk_add_f32 v[94:95], v[94:95], 1.0 op_sel_hi:[1,0]
	v_pk_add_f32 v[104:105], v[104:105], 1.0 op_sel_hi:[1,0]
	v_pk_add_f32 v[102:103], v[102:103], 1.0 op_sel_hi:[1,0]
	v_pk_mul_f32 v[2:3], v[2:3], v[132:133] op_sel_hi:[1,0]
	v_pk_mul_f32 v[4:5], v[4:5], v[132:133] op_sel_hi:[1,0]
	v_pk_mul_f32 v[6:7], v[6:7], v[132:133] op_sel_hi:[1,0]
	v_pk_mul_f32 v[8:9], v[8:9], v[132:133] op_sel_hi:[1,0]
	v_pk_mul_f32 v[10:11], v[10:11], v[132:133] op_sel_hi:[1,0]
	v_pk_mul_f32 v[12:13], v[12:13], v[132:133] op_sel_hi:[1,0]
	v_pk_mul_f32 v[14:15], v[14:15], v[132:133] op_sel_hi:[1,0]
	v_pk_mul_f32 v[16:17], v[16:17], v[132:133] op_sel_hi:[1,0]
	v_pk_fma_f32 v[2:3], v[138:139], v[2:3], v[134:135]
	v_pk_fma_f32 v[4:5], v[140:141], v[4:5], v[136:137]
	v_pk_fma_f32 v[6:7], v[86:87], v[6:7], v[82:83]
	v_pk_fma_f32 v[8:9], v[88:89], v[8:9], v[84:85]
	v_pk_fma_f32 v[10:11], v[94:95], v[10:11], v[90:91]
	v_pk_fma_f32 v[12:13], v[96:97], v[12:13], v[92:93]
	v_pk_fma_f32 v[14:15], v[102:103], v[14:15], v[98:99]
	v_pk_fma_f32 v[16:17], v[104:105], v[16:17], v[100:101]
	v_cvt_pk_bf16_f32 v2, v2, v3
	v_cvt_pk_bf16_f32 v3, v4, v5
	v_cvt_pk_bf16_f32 v6, v6, v7
	v_cvt_pk_bf16_f32 v7, v8, v9
	v_cvt_pk_bf16_f32 v10, v10, v11
	v_cvt_pk_bf16_f32 v11, v12, v13
	v_cvt_pk_bf16_f32 v14, v14, v15
	v_cvt_pk_bf16_f32 v15, v16, v17
	global_store_dwordx2 v[78:79], v[2:3], off
	global_store_dwordx2 v[78:79], v[6:7], off offset:512
	global_store_dwordx2 v[78:79], v[10:11], off offset:1024
	global_store_dwordx2 v[78:79], v[14:15], off offset:1536
	s_andn2_b64 vcc, exec, s[14:15]
	s_cbranch_vccnz .Lpn1_row1_done
	v_pk_add_f32 v[112:113], v[112:113], 1.0 op_sel_hi:[1,0]
	v_pk_add_f32 v[110:111], v[110:111], 1.0 op_sel_hi:[1,0]
	v_pk_add_f32 v[120:121], v[120:121], 1.0 op_sel_hi:[1,0]
	v_pk_add_f32 v[118:119], v[118:119], 1.0 op_sel_hi:[1,0]
	v_pk_add_f32 v[128:129], v[128:129], 1.0 op_sel_hi:[1,0]
	v_pk_add_f32 v[126:127], v[126:127], 1.0 op_sel_hi:[1,0]
	v_pk_add_f32 v[152:153], v[152:153], 1.0 op_sel_hi:[1,0]
	v_pk_add_f32 v[150:151], v[150:151], 1.0 op_sel_hi:[1,0]
	v_pk_mul_f32 v[46:47], v[46:47], v[130:131] op_sel_hi:[1,0]
	v_pk_mul_f32 v[48:49], v[48:49], v[130:131] op_sel_hi:[1,0]
	v_pk_mul_f32 v[42:43], v[42:43], v[130:131] op_sel_hi:[1,0]
	v_pk_mul_f32 v[44:45], v[44:45], v[130:131] op_sel_hi:[1,0]
	v_pk_mul_f32 v[38:39], v[38:39], v[130:131] op_sel_hi:[1,0]
	v_pk_mul_f32 v[40:41], v[40:41], v[130:131] op_sel_hi:[1,0]
	v_pk_mul_f32 v[34:35], v[34:35], v[130:131] op_sel_hi:[1,0]
	v_pk_mul_f32 v[36:37], v[36:37], v[130:131] op_sel_hi:[1,0]
	v_pk_fma_f32 v[46:47], v[46:47], v[110:111], v[106:107]
	v_pk_fma_f32 v[48:49], v[48:49], v[112:113], v[108:109]
	v_pk_fma_f32 v[42:43], v[42:43], v[118:119], v[114:115]
	v_pk_fma_f32 v[44:45], v[44:45], v[120:121], v[116:117]
	v_pk_fma_f32 v[38:39], v[38:39], v[126:127], v[122:123]
	v_pk_fma_f32 v[40:41], v[40:41], v[128:129], v[124:125]
	v_pk_fma_f32 v[34:35], v[34:35], v[150:151], v[146:147]
	v_pk_fma_f32 v[36:37], v[36:37], v[152:153], v[148:149]
	v_cvt_pk_bf16_f32 v46, v46, v47
	v_cvt_pk_bf16_f32 v47, v48, v49
	v_cvt_pk_bf16_f32 v42, v42, v43
	v_cvt_pk_bf16_f32 v43, v44, v45
	v_cvt_pk_bf16_f32 v38, v38, v39
	v_cvt_pk_bf16_f32 v39, v40, v41
	v_cvt_pk_bf16_f32 v34, v34, v35
	v_cvt_pk_bf16_f32 v35, v36, v37
	global_store_dwordx2 v142, v[46:47], s[16:17]
	global_store_dwordx2 v142, v[42:43], s[16:17] offset:512
	global_store_dwordx2 v142, v[38:39], s[16:17] offset:1024
	global_store_dwordx2 v142, v[34:35], s[16:17] offset:1536

.Lpn1_pf_top:
	s_waitcnt vmcnt(8)
	v_mov_b64_e32 v[2:3], v[18:19]
	v_mov_b64_e32 v[4:5], v[20:21]
	v_mov_b64_e32 v[6:7], v[22:23]
	v_mov_b64_e32 v[8:9], v[24:25]
	v_mov_b64_e32 v[10:11], v[26:27]
	v_mov_b64_e32 v[12:13], v[28:29]
	v_mov_b64_e32 v[14:15], v[30:31]
	v_mov_b64_e32 v[16:17], v[32:33]
	v_mov_b64_e32 v[46:47], v[62:63]
	v_mov_b64_e32 v[48:49], v[64:65]
	v_mov_b64_e32 v[42:43], v[54:55]
	v_mov_b64_e32 v[44:45], v[56:57]
	v_mov_b64_e32 v[38:39], v[58:59]
	v_mov_b64_e32 v[40:41], v[60:61]
	v_mov_b64_e32 v[34:35], v[50:51]
	v_mov_b64_e32 v[36:37], v[52:53]
	s_branch .LBB0_210

	.amdhsa_kernel _Z4mega4Args
		.amdhsa_group_segment_fixed_size 0
		.amdhsa_private_segment_fixed_size 0
		.amdhsa_kernarg_size 472
		.amdhsa_user_sgpr_count 2
		.amdhsa_user_sgpr_dispatch_ptr 0
		.amdhsa_user_sgpr_queue_ptr 0
		.amdhsa_user_sgpr_kernarg_segment_ptr 1
		.amdhsa_user_sgpr_dispatch_id 0
		.amdhsa_user_sgpr_kernarg_preload_length 0
		.amdhsa_user_sgpr_kernarg_preload_offset 0
		.amdhsa_user_sgpr_private_segment_size 0
		.amdhsa_uses_dynamic_stack 0
		.amdhsa_enable_private_segment 0
		.amdhsa_system_sgpr_workgroup_id_x 1
		.amdhsa_system_sgpr_workgroup_id_y 0
		.amdhsa_system_sgpr_workgroup_id_z 0
		.amdhsa_system_sgpr_workgroup_info 0
		.amdhsa_system_vgpr_workitem_id 2
		.amdhsa_next_free_vgpr 256
		.amdhsa_next_free_sgpr 102
		.amdhsa_accum_offset 256
		.amdhsa_reserve_vcc 1
		.amdhsa_float_round_mode_32 0
		.amdhsa_float_round_mode_16_64 0
		.amdhsa_float_denorm_mode_32 3
		.amdhsa_float_denorm_mode_16_64 3
		.amdhsa_dx10_clamp 1
		.amdhsa_ieee_mode 1
		.amdhsa_fp16_overflow 0
		.amdhsa_tg_split 0
		.amdhsa_exception_fp_ieee_invalid_op 0
		.amdhsa_exception_fp_denorm_src 0
		.amdhsa_exception_fp_ieee_div_zero 0
		.amdhsa_exception_fp_ieee_overflow 0
		.amdhsa_exception_fp_ieee_underflow 0
		.amdhsa_exception_fp_ieee_inexact 0
		.amdhsa_exception_int_div_zero 0
	.end_amdhsa_kernel

amdhsa.kernels:
  - .agpr_count:     0
    .args:
      - .offset:         0
        .size:           216
        .value_kind:     by_value
      - .offset:         216
        .size:           4
        .value_kind:     hidden_block_count_x
      - .offset:         220
        .size:           4
        .value_kind:     hidden_block_count_y
      - .offset:         224
        .size:           4
        .value_kind:     hidden_block_count_z
      - .offset:         228
        .size:           2
        .value_kind:     hidden_group_size_x
      - .offset:         230
        .size:           2
        .value_kind:     hidden_group_size_y
      - .offset:         232
        .size:           2
        .value_kind:     hidden_group_size_z
      - .offset:         234
        .size:           2
        .value_kind:     hidden_remainder_x
      - .offset:         236
        .size:           2
        .value_kind:     hidden_remainder_y
      - .offset:         238
        .size:           2
        .value_kind:     hidden_remainder_z
      - .offset:         256
        .size:           8
        .value_kind:     hidden_global_offset_x
      - .offset:         264
        .size:           8
        .value_kind:     hidden_global_offset_y
      - .offset:         272
        .size:           8
        .value_kind:     hidden_global_offset_z
      - .offset:         280
        .size:           2
        .value_kind:     hidden_grid_dims
      - .offset:         304
        .size:           8
        .value_kind:     hidden_multigrid_sync_arg
      - .offset:         336
        .size:           4
        .value_kind:     hidden_dynamic_lds_size
    .group_segment_fixed_size: 0
    .kernarg_segment_align: 8
    .kernarg_segment_size: 472
    .language:       OpenCL C
    .language_version:
      - 2
      - 0
    .max_flat_workgroup_size: 512
    .name:           _Z4mega4Args
    .private_segment_fixed_size: 0
    .sgpr_count:     108
    .sgpr_spill_count: 136
    .symbol:         _Z4mega4Args.kd
    .uniform_work_group_size: 1
    .uses_dynamic_stack: false
    .vgpr_count:     256
    .vgpr_spill_count: 0
    .wavefront_size: 64
